# sg_task: the eight per-column-block v_gain loads hoisted in front of the column loop (their vmcnt(0) waits were also draining the previous block's stores)
# baseline (speedup 1.0000x reference)
; #define LAS __attribute__((address_space(3)))
; __device__ __forceinline__ void sg_task(const bf16* Z, bf16* YC, const ss_t* ssV, const float* vgain, const float* sw, const float* sb, LAS unsigned char* tile, int task, int tid) {
;     ...
;     const int g = task & 7, n = (task >> 3) & 31, b = task >> 8;
;     const int tok0 = b * SEQ + n * 128;
;     const int p = wave * 16 + fr; const size_t tokp = (size_t)(tok0 + p);
;     bf16x8 tv[4];
; #pragma unroll
;     for (int i = 0; i < 4; ++i) { const int id = tid + NTHR * i, q = id >> 4, ch = id & 15; tv[i] = *(const bf16x8*)(Z + (size_t)(tok0 + q) * NZ + 4096 + g * 128 + ch * 8); }
;     f32x4 w0[4], w1[4]; unsigned long long sq[4][8];
; #pragma unroll
;     for (int kk = 0; kk < 4; ++kk) { const int q0 = kk * 32 + fq * 8; const float* wp = sw + (size_t)(g * 128 + p) * 128 + q0; const ss_t* sp = ssV + tok0 + q0;
;         w0[kk] = *(const f32x4*)wp; w1[kk] = *(const f32x4*)(wp + 4);
; #pragma unroll
;         for (int e = 0; e < 8; ++e) sq[kk][e] = sp[e]; }
;     u32x2 uu[8];
; #pragma unroll
;     for (int cb = 0; cb < 8; ++cb) uu[cb] = *(const u32x2*)(Z + tokp * NZ + 3072 + g * 128 + cb * 16 + fq * 4);
;     const float bias = sb[g * 128 + p];
; #pragma unroll
;     for (int i = 0; i < 4; ++i) { const int id = tid + NTHR * i, q = id >> 4, ch = id & 15; *(LAS bf16x8*)(tile + off_b(q, ch)) = tv[i]; }
.LBB0_1541:
	v_mov_b32_e32 v123, v218
	s_and_b32 s4, s9, 0xffffff80
	v_ashrrev_i32_e32 v0, 2, v123
	v_ashrrev_i32_e32 v141, 4, v123
	v_bfi_b32 v8, -16, v0, v123
	s_and_b32 s2, s8, 0x380
	v_add_u32_e32 v0, s4, v141
	v_mov_b64_e32 v[102:103], s[34:35]
	v_add_u32_e32 v6, 0x200, v123
	v_mad_i64_i32 v[2:3], s[22:23], v0, s36, v[102:103]
	s_lshl_b32 s18, s2, 1
	v_lshlrev_b32_e32 v0, 4, v123
	v_ashrrev_i32_e32 v142, 4, v6
	v_lshl_add_u64 v[2:3], v[2:3], 0, s[18:19]
	v_and_b32_e32 v0, 0xf0, v0
	v_add_u32_e32 v6, s4, v142
	v_lshl_add_u64 v[2:3], v[2:3], 0, v[0:1]
	v_mad_i64_i32 v[6:7], s[22:23], v6, s36, v[102:103]
	v_add_co_u32_e32 v2, vcc, s26, v2
	v_lshl_add_u64 v[6:7], v[6:7], 0, s[18:19]
	s_nop 0
	v_addc_co_u32_e32 v3, vcc, 0, v3, vcc
	v_lshl_add_u64 v[6:7], v[6:7], 0, v[0:1]
	v_add_co_u32_e32 v6, vcc, s26, v6
	global_load_dwordx4 v[2:5], v[2:3], off
	s_nop 0
	v_addc_co_u32_e32 v7, vcc, 0, v7, vcc
	global_load_dwordx4 v[74:77], v[6:7], off
	v_add_u32_e32 v6, 0x400, v123
	v_ashrrev_i32_e32 v143, 4, v6
	v_add_u32_e32 v6, s4, v143
	v_mad_i64_i32 v[6:7], s[22:23], v6, s36, v[102:103]
	v_lshl_add_u64 v[6:7], v[6:7], 0, s[18:19]
	v_lshl_add_u64 v[6:7], v[6:7], 0, v[0:1]
	v_add_co_u32_e32 v6, vcc, s26, v6
	v_add_u32_e32 v120, s2, v8
	s_nop 0
	v_addc_co_u32_e32 v7, vcc, 0, v7, vcc
	global_load_dwordx4 v[78:81], v[6:7], off
	v_add_u32_e32 v6, 0x600, v123
	v_ashrrev_i32_e32 v144, 4, v6
	v_add_u32_e32 v6, s4, v144
	v_mad_i64_i32 v[6:7], s[22:23], v6, s36, v[102:103]
	v_lshl_add_u64 v[6:7], v[6:7], 0, s[18:19]
	v_lshl_add_u64 v[6:7], v[6:7], 0, v[0:1]
	v_add_co_u32_e32 v6, vcc, s26, v6
	v_ashrrev_i32_e32 v121, 31, v120
	s_nop 0
	v_addc_co_u32_e32 v7, vcc, 0, v7, vcc
	global_load_dwordx4 v[82:85], v[6:7], off
	v_bfe_u32 v124, v123, 4, 2
	v_lshlrev_b64 v[6:7], 9, v[120:121]
	s_ashr_i32 s5, s4, 31
	v_add_u32_e32 v116, s4, v8
	s_waitcnt lgkmcnt(0)
	v_lshl_add_u64 v[6:7], s[58:59], 0, v[6:7]
	s_lshl_b64 s[4:5], s[4:5], 3
	v_lshlrev_b32_e32 v8, 5, v124
	v_mov_b32_e32 v9, v1
	s_add_u32 s4, s6, s4
	s_waitcnt vmcnt(15)
	v_lshl_add_u64 v[18:19], v[6:7], 0, v[8:9]
	v_lshlrev_b32_e32 v34, 6, v124
	s_addc_u32 s5, s7, s5
	global_load_dwordx4 v[90:93], v[18:19], off offset:16
	global_load_dwordx4 v[98:101], v[18:19], off
	global_load_dwordx4 v[94:97], v34, s[4:5] offset:48
	global_load_dwordx4 v[126:129], v34, s[4:5] offset:32
	global_load_dwordx4 v[130:133], v34, s[4:5] offset:16
	global_load_dwordx4 v[134:137], v34, s[4:5]
	global_load_dwordx4 v[6:9], v[18:19], off offset:144
	global_load_dwordx4 v[62:65], v[18:19], off offset:128
	global_load_dwordx4 v[58:61], v34, s[4:5] offset:304
	global_load_dwordx4 v[70:73], v34, s[4:5] offset:288
	global_load_dwordx4 v[66:69], v34, s[4:5] offset:272
	global_load_dwordx4 v[86:89], v34, s[4:5] offset:256
	global_load_dwordx4 v[10:13], v[18:19], off offset:272
	global_load_dwordx4 v[42:45], v[18:19], off offset:256
	global_load_dwordx4 v[38:41], v34, s[4:5] offset:560
	global_load_dwordx4 v[50:53], v34, s[4:5] offset:544
	global_load_dwordx4 v[46:49], v34, s[4:5] offset:528
	global_load_dwordx4 v[54:57], v34, s[4:5] offset:512
	global_load_dwordx4 v[14:17], v[18:19], off offset:400
	global_load_dwordx4 v[22:25], v[18:19], off offset:384
	s_nop 0
	global_load_dwordx4 v[18:21], v34, s[4:5] offset:816
	global_load_dwordx4 v[30:33], v34, s[4:5] offset:800
	global_load_dwordx4 v[26:29], v34, s[4:5] offset:784
	s_nop 0
	global_load_dwordx4 v[34:37], v34, s[4:5] offset:768
	v_mad_i64_i32 v[102:103], s[4:5], v116, s36, v[102:103]
	v_lshlrev_b32_e32 v0, 3, v124
	v_lshl_add_u64 v[102:103], v[102:103], 0, s[18:19]
	v_lshl_add_u64 v[102:103], v[102:103], 0, v[0:1]
	s_mov_b64 s[4:5], 0x1800
	v_lshl_add_u64 v[138:139], v[102:103], 0, s[4:5]
	v_add_co_u32_e32 v102, vcc, s3, v102
	v_and_b32_e32 v140, 15, v123
	s_nop 0
	v_addc_co_u32_e32 v103, vcc, 0, v103, vcc
	global_load_dwordx2 v[118:119], v[102:103], off offset:2048
	global_load_dwordx2 v[114:115], v[138:139], off offset:32
	global_load_dwordx2 v[112:113], v[138:139], off offset:64
	global_load_dwordx2 v[110:111], v[138:139], off offset:96
	global_load_dwordx2 v[108:109], v[138:139], off offset:128
	global_load_dwordx2 v[106:107], v[138:139], off offset:160
	global_load_dwordx2 v[104:105], v[138:139], off offset:192
	global_load_dwordx2 v[102:103], v[138:139], off offset:224
	s_load_dwordx2 s[4:5], s[46:47], 0xa0
	v_bfe_u32 v138, v141, 2, 2
	v_lshlrev_b32_e32 v0, 8, v141
	v_and_b32_e32 v125, 63, v123
	v_lshlrev_b32_e32 v122, 3, v123
	s_waitcnt lgkmcnt(0)
	v_lshl_add_u64 v[120:121], v[120:121], 2, s[4:5]
	global_load_dword v120, v[120:121], off
	v_lshlrev_b32_e32 v121, 2, v141
	v_and_b32_e32 v121, 12, v121
	v_bitop3_b32 v121, v121, v140, v138 bitop3:0x36
	v_lshlrev_b32_e32 v121, 4, v121
	v_add3_u32 v0, 0, v121, v0
	v_ashrrev_i32_e32 v117, 31, v116
	s_add_i32 s10, s10, s24
	s_add_i32 s9, s9, s25
	s_add_i32 s8, s8, s11
	s_cmpk_lt_i32 s10, 0x200
	s_waitcnt vmcnt(36)
	ds_write_b128 v0, v[2:5]
	v_lshlrev_b32_e32 v2, 2, v142
	v_and_b32_e32 v2, 12, v2
	v_bfe_u32 v3, v142, 2, 2
	v_bitop3_b32 v2, v2, v140, v3 bitop3:0x36
	v_lshlrev_b32_e32 v0, 8, v142
	v_lshlrev_b32_e32 v2, 4, v2
	v_add3_u32 v0, 0, v2, v0
	v_lshlrev_b32_e32 v2, 2, v143
	v_and_b32_e32 v2, 12, v2
	v_bfe_u32 v3, v143, 2, 2
	v_bitop3_b32 v2, v2, v140, v3 bitop3:0x36
	s_waitcnt vmcnt(35)
	ds_write_b128 v0, v[74:77]
	v_lshlrev_b32_e32 v0, 8, v143
	v_lshlrev_b32_e32 v2, 4, v2
	v_add3_u32 v0, 0, v2, v0
	v_lshlrev_b32_e32 v2, 2, v144
	v_and_b32_e32 v2, 12, v2
	v_bfe_u32 v3, v144, 2, 2
	v_bitop3_b32 v2, v2, v140, v3 bitop3:0x36
	s_waitcnt vmcnt(34)
	ds_write_b128 v0, v[78:81]
	v_lshlrev_b32_e32 v0, 8, v144
	v_lshlrev_b32_e32 v2, 4, v2
	v_add3_u32 v0, 0, v2, v0
	s_waitcnt vmcnt(27)
; __device__ __forceinline__ unsigned cvt_pk_bf16(float lo, float hi) { unsigned r; asm volatile("v_cvt_pk_bf16_f32 %0, %1, %2" : "=v"(r) : "v"(lo), "v"(hi)); return r; }
; #define LAS __attribute__((address_space(3)))
; __device__ __forceinline__ void sg_task(const bf16* Z, bf16* YC, const ss_t* ssV, const float* vgain, const float* sw, const float* sb, LAS unsigned char* tile, int task, int tid) {
;     ...
;     for (int i = 0; i < 4; ++i) { const int id = tid + NTHR * i, q = id >> 4, ch = id & 15; *(LAS bf16x8*)(tile + off_b(q, ch)) = tv[i]; }
;     bf16x8 bfrag[4];
; #pragma unroll
;     for (int kk = 0; kk < 4; ++kk) {
;         float a[8];
; #pragma unroll
;         for (int e = 0; e < 4; ++e) { a[e] = w0[kk][e] * rsqrtf((float)(long long)sq[kk][e] * (1.0f / 1048576.0f) * (1.0f / 1024.0f) + EPS);
;                                       a[4 + e] = w1[kk][e] * rsqrtf((float)(long long)sq[kk][4 + e] * (1.0f / 1048576.0f) * (1.0f / 1024.0f) + EPS); }
;         u32x4 w; w.x = cvt_pk_bf16(a[0], a[1]); w.y = cvt_pk_bf16(a[2], a[3]); w.z = cvt_pk_bf16(a[4], a[5]); w.w = cvt_pk_bf16(a[6], a[7]);
;         bfrag[kk] = __builtin_bit_cast(bf16x8, w);
	v_ffbh_i32_e32 v2, v135
	v_add_u32_e32 v2, -1, v2
	ds_write_b128 v0, v[82:85]
	v_xor_b32_e32 v0, v134, v135
	v_ashrrev_i32_e32 v0, 31, v0
	v_add_u32_e32 v0, 32, v0
	v_min_u32_e32 v0, v2, v0
	v_lshlrev_b64 v[2:3], v0, v[134:135]
	v_min_u32_e32 v2, 1, v2
	v_or_b32_e32 v2, v3, v2
	v_cvt_f32_i32_e32 v2, v2
	v_sub_u32_e32 v0, 32, v0
	v_ffbh_i32_e32 v3, v127
	v_add_u32_e32 v3, -1, v3
	v_ldexp_f32 v0, v2, v0
	v_mul_f32_e32 v0, 0x35800000, v0
	v_fmamk_f32 v0, v0, 0x3a800000, v222
	v_cmp_gt_f32_e32 vcc, s13, v0
	v_mul_f32_e32 v2, 0x4b800000, v0
	s_nop 0
	v_cndmask_b32_e32 v0, v0, v2, vcc
	v_rsq_f32_e32 v0, v0
	s_nop 0
	v_mul_f32_e32 v2, 0x45800000, v0
	v_cndmask_b32_e32 v0, v0, v2, vcc
	v_xor_b32_e32 v2, v126, v127
	v_ashrrev_i32_e32 v2, 31, v2
	v_add_u32_e32 v2, 32, v2
	v_min_u32_e32 v4, v3, v2
	v_lshlrev_b64 v[2:3], v4, v[126:127]
	v_min_u32_e32 v2, 1, v2
	v_or_b32_e32 v2, v3, v2
	v_cvt_f32_i32_e32 v2, v2
	v_sub_u32_e32 v3, 32, v4
	v_mul_f32_e32 v0, v98, v0
	v_ldexp_f32 v2, v2, v3
	v_mul_f32_e32 v2, 0x35800000, v2
	v_fmamk_f32 v2, v2, 0x3a800000, v222
	v_cmp_gt_f32_e32 vcc, s13, v2
	v_mul_f32_e32 v3, 0x4b800000, v2
	s_nop 0
	v_cndmask_b32_e32 v2, v2, v3, vcc
	v_rsq_f32_e32 v2, v2
	s_nop 0
	v_mul_f32_e32 v3, 0x45800000, v2
	v_cndmask_b32_e32 v2, v2, v3, vcc
	v_mul_f32_e32 v4, v90, v2
	v_xor_b32_e32 v2, v136, v137
	v_ashrrev_i32_e32 v2, 31, v2
	v_ffbh_i32_e32 v3, v137
	v_add_u32_e32 v2, 32, v2
	v_add_u32_e32 v3, -1, v3
	v_min_u32_e32 v5, v3, v2
	v_lshlrev_b64 v[2:3], v5, v[136:137]
	v_min_u32_e32 v2, 1, v2
	v_or_b32_e32 v2, v3, v2
	v_cvt_f32_i32_e32 v2, v2
	v_sub_u32_e32 v3, 32, v5
	v_ldexp_f32 v2, v2, v3
	v_mul_f32_e32 v2, 0x35800000, v2
	v_fmamk_f32 v2, v2, 0x3a800000, v222
	v_cmp_gt_f32_e32 vcc, s13, v2
	v_mul_f32_e32 v3, 0x4b800000, v2
	s_nop 0
	v_cndmask_b32_e32 v2, v2, v3, vcc
	v_rsq_f32_e32 v2, v2
	s_nop 0
	v_mul_f32_e32 v3, 0x45800000, v2
	v_cndmask_b32_e32 v2, v2, v3, vcc
	v_mul_f32_e32 v5, v99, v2
	v_xor_b32_e32 v2, v128, v129
	v_ashrrev_i32_e32 v2, 31, v2
	v_ffbh_i32_e32 v3, v129
	v_add_u32_e32 v2, 32, v2
	v_add_u32_e32 v3, -1, v3
	v_min_u32_e32 v74, v3, v2
	v_lshlrev_b64 v[2:3], v74, v[128:129]
	v_min_u32_e32 v2, 1, v2
	v_or_b32_e32 v2, v3, v2
	v_cvt_f32_i32_e32 v2, v2
	v_sub_u32_e32 v3, 32, v74
	v_ldexp_f32 v2, v2, v3
	v_mul_f32_e32 v2, 0x35800000, v2
	v_fmamk_f32 v2, v2, 0x3a800000, v222
	v_cmp_gt_f32_e32 vcc, s13, v2
	v_mul_f32_e32 v3, 0x4b800000, v2
	s_nop 0
	v_cndmask_b32_e32 v2, v2, v3, vcc
	v_rsq_f32_e32 v2, v2
	s_nop 0
	v_mul_f32_e32 v3, 0x45800000, v2
	v_cndmask_b32_e32 v2, v2, v3, vcc
	v_mul_f32_e32 v74, v91, v2
	v_xor_b32_e32 v2, v130, v131
	v_ashrrev_i32_e32 v2, 31, v2
	v_ffbh_i32_e32 v3, v131
	v_add_u32_e32 v2, 32, v2
	v_add_u32_e32 v3, -1, v3
	v_min_u32_e32 v75, v3, v2
	v_lshlrev_b64 v[2:3], v75, v[130:131]
	v_min_u32_e32 v2, 1, v2
	v_or_b32_e32 v2, v3, v2
	v_cvt_f32_i32_e32 v2, v2
	v_sub_u32_e32 v3, 32, v75
	v_ldexp_f32 v2, v2, v3
	v_mul_f32_e32 v2, 0x35800000, v2
	v_fmamk_f32 v2, v2, 0x3a800000, v222
	v_cmp_gt_f32_e32 vcc, s13, v2
	v_mul_f32_e32 v3, 0x4b800000, v2
	s_nop 0
	v_cndmask_b32_e32 v2, v2, v3, vcc
	v_rsq_f32_e32 v2, v2
	s_nop 0
	v_mul_f32_e32 v3, 0x45800000, v2
	v_cndmask_b32_e32 v2, v2, v3, vcc
	v_mul_f32_e32 v75, v100, v2
	v_xor_b32_e32 v2, v94, v95
	v_ashrrev_i32_e32 v2, 31, v2
	v_ffbh_i32_e32 v3, v95
	v_add_u32_e32 v2, 32, v2
	v_add_u32_e32 v3, -1, v3
	v_min_u32_e32 v76, v3, v2
	v_lshlrev_b64 v[2:3], v76, v[94:95]
	v_min_u32_e32 v2, 1, v2
	v_or_b32_e32 v2, v3, v2
	v_cvt_f32_i32_e32 v2, v2
	v_sub_u32_e32 v3, 32, v76
	v_ldexp_f32 v2, v2, v3
	v_mul_f32_e32 v2, 0x35800000, v2
	v_fmamk_f32 v2, v2, 0x3a800000, v222
	v_cmp_gt_f32_e32 vcc, s13, v2
	v_mul_f32_e32 v3, 0x4b800000, v2
	s_nop 0
	v_cndmask_b32_e32 v2, v2, v3, vcc
	v_rsq_f32_e32 v2, v2
	s_nop 0
	v_mul_f32_e32 v3, 0x45800000, v2
	v_cndmask_b32_e32 v2, v2, v3, vcc
	v_mul_f32_e32 v76, v92, v2
	v_xor_b32_e32 v2, v132, v133
	v_ashrrev_i32_e32 v2, 31, v2
	v_ffbh_i32_e32 v3, v133
	v_add_u32_e32 v2, 32, v2
	v_add_u32_e32 v3, -1, v3
	v_min_u32_e32 v77, v3, v2
	v_lshlrev_b64 v[2:3], v77, v[132:133]
	v_min_u32_e32 v2, 1, v2
	v_or_b32_e32 v2, v3, v2
	v_cvt_f32_i32_e32 v2, v2
	v_sub_u32_e32 v3, 32, v77
	v_ldexp_f32 v2, v2, v3
	v_mul_f32_e32 v2, 0x35800000, v2
	v_fmamk_f32 v2, v2, 0x3a800000, v222
	v_cmp_gt_f32_e32 vcc, s13, v2
	v_mul_f32_e32 v3, 0x4b800000, v2
	s_nop 0
	v_cndmask_b32_e32 v2, v2, v3, vcc
	v_rsq_f32_e32 v2, v2
	s_nop 0
	v_mul_f32_e32 v3, 0x45800000, v2
	v_cndmask_b32_e32 v2, v2, v3, vcc
	v_mul_f32_e32 v77, v101, v2
	v_xor_b32_e32 v2, v96, v97
	v_ashrrev_i32_e32 v2, 31, v2
	v_ffbh_i32_e32 v3, v97
	v_add_u32_e32 v2, 32, v2
	v_add_u32_e32 v3, -1, v3
	v_min_u32_e32 v78, v3, v2
	v_lshlrev_b64 v[2:3], v78, v[96:97]
	v_min_u32_e32 v2, 1, v2
	v_or_b32_e32 v2, v3, v2
	v_cvt_f32_i32_e32 v2, v2
	v_sub_u32_e32 v3, 32, v78
	v_ldexp_f32 v2, v2, v3
	v_mul_f32_e32 v2, 0x35800000, v2
	v_fmamk_f32 v2, v2, 0x3a800000, v222
	v_cmp_gt_f32_e32 vcc, s13, v2
	v_mul_f32_e32 v3, 0x4b800000, v2
	s_nop 0
	v_cndmask_b32_e32 v2, v2, v3, vcc
	v_rsq_f32_e32 v2, v2
	s_nop 0
	v_mul_f32_e32 v3, 0x45800000, v2
	v_cndmask_b32_e32 v2, v2, v3, vcc
	v_mul_f32_e32 v78, v93, v2
	v_cvt_pk_bf16_f32 v2, v0, v5
	s_waitcnt vmcnt(21)
; __device__ __forceinline__ unsigned cvt_pk_bf16(float lo, float hi) { unsigned r; asm volatile("v_cvt_pk_bf16_f32 %0, %1, %2" : "=v"(r) : "v"(lo), "v"(hi)); return r; }
; __device__ __forceinline__ void sg_task(const bf16* Z, bf16* YC, const ss_t* ssV, const float* vgain, const float* sw, const float* sb, LAS unsigned char* tile, int task, int tid) {
;     ...
;     for (int kk = 0; kk < 4; ++kk) {
;         float a[8];
; #pragma unroll
;         for (int e = 0; e < 4; ++e) { a[e] = w0[kk][e] * rsqrtf((float)(long long)sq[kk][e] * (1.0f / 1048576.0f) * (1.0f / 1024.0f) + EPS);
;                                       a[4 + e] = w1[kk][e] * rsqrtf((float)(long long)sq[kk][4 + e] * (1.0f / 1048576.0f) * (1.0f / 1024.0f) + EPS); }
;         u32x4 w; w.x = cvt_pk_bf16(a[0], a[1]); w.y = cvt_pk_bf16(a[2], a[3]); w.z = cvt_pk_bf16(a[4], a[5]); w.w = cvt_pk_bf16(a[6], a[7]);
;         bfrag[kk] = __builtin_bit_cast(bf16x8, w);
	v_xor_b32_e32 v0, v86, v87
	v_cvt_pk_bf16_f32 v3, v75, v77
	v_cvt_pk_bf16_f32 v4, v4, v74
	v_ashrrev_i32_e32 v0, 31, v0
	v_ffbh_i32_e32 v74, v87
	v_add_u32_e32 v0, 32, v0
	v_add_u32_e32 v74, -1, v74
	v_min_u32_e32 v0, v74, v0
	v_lshlrev_b64 v[74:75], v0, v[86:87]
	v_min_u32_e32 v74, 1, v74
	v_or_b32_e32 v74, v75, v74
	v_cvt_f32_i32_e32 v74, v74
	v_sub_u32_e32 v0, 32, v0
	v_cvt_pk_bf16_f32 v5, v76, v78
	v_ldexp_f32 v0, v74, v0
	v_mul_f32_e32 v0, 0x35800000, v0
	v_fmamk_f32 v0, v0, 0x3a800000, v222
	v_cmp_gt_f32_e32 vcc, s13, v0
	v_mul_f32_e32 v74, 0x4b800000, v0
	s_nop 0
	v_cndmask_b32_e32 v0, v0, v74, vcc
	v_rsq_f32_e32 v0, v0
	s_nop 0
	v_mul_f32_e32 v74, 0x45800000, v0
	v_cndmask_b32_e32 v0, v0, v74, vcc
	v_mul_f32_e32 v0, v62, v0
	v_xor_b32_e32 v62, v70, v71
	v_ashrrev_i32_e32 v62, 31, v62
	v_ffbh_i32_e32 v74, v71
	v_add_u32_e32 v62, 32, v62
	v_add_u32_e32 v74, -1, v74
	v_min_u32_e32 v62, v74, v62
	v_lshlrev_b64 v[70:71], v62, v[70:71]
	v_min_u32_e32 v70, 1, v70
	v_or_b32_e32 v70, v71, v70
	v_cvt_f32_i32_e32 v70, v70
	v_sub_u32_e32 v62, 32, v62
	v_ldexp_f32 v62, v70, v62
	v_mul_f32_e32 v62, 0x35800000, v62
	v_fmamk_f32 v62, v62, 0x3a800000, v222
	v_cmp_gt_f32_e32 vcc, s13, v62
	v_mul_f32_e32 v70, 0x4b800000, v62
	s_nop 0
	v_cndmask_b32_e32 v62, v62, v70, vcc
	v_rsq_f32_e32 v62, v62
	s_nop 0
	v_mul_f32_e32 v70, 0x45800000, v62
	v_cndmask_b32_e32 v62, v62, v70, vcc
	v_mul_f32_e32 v74, v6, v62
	v_xor_b32_e32 v6, v88, v89
	v_ashrrev_i32_e32 v6, 31, v6
	v_ffbh_i32_e32 v62, v89
	v_add_u32_e32 v6, 32, v6
	v_add_u32_e32 v62, -1, v62
	v_min_u32_e32 v6, v62, v6
	v_lshlrev_b64 v[70:71], v6, v[88:89]
	v_min_u32_e32 v62, 1, v70
	v_or_b32_e32 v62, v71, v62
	v_cvt_f32_i32_e32 v62, v62
	v_sub_u32_e32 v6, 32, v6
	v_ldexp_f32 v6, v62, v6
	v_mul_f32_e32 v6, 0x35800000, v6
	v_fmamk_f32 v6, v6, 0x3a800000, v222
	v_cmp_gt_f32_e32 vcc, s13, v6
	v_mul_f32_e32 v62, 0x4b800000, v6
	s_nop 0
	v_cndmask_b32_e32 v6, v6, v62, vcc
	v_rsq_f32_e32 v6, v6
	s_nop 0
	v_mul_f32_e32 v62, 0x45800000, v6
	v_cndmask_b32_e32 v6, v6, v62, vcc
	v_mul_f32_e32 v70, v63, v6
	v_xor_b32_e32 v6, v72, v73
	v_ashrrev_i32_e32 v6, 31, v6
	v_ffbh_i32_e32 v62, v73
	v_add_u32_e32 v6, 32, v6
	v_add_u32_e32 v62, -1, v62
	v_min_u32_e32 v6, v62, v6
	v_lshlrev_b64 v[62:63], v6, v[72:73]
	v_min_u32_e32 v62, 1, v62
	v_or_b32_e32 v62, v63, v62
	v_cvt_f32_i32_e32 v62, v62
	v_sub_u32_e32 v6, 32, v6
	v_ldexp_f32 v6, v62, v6
	v_mul_f32_e32 v6, 0x35800000, v6
	v_fmamk_f32 v6, v6, 0x3a800000, v222
	v_cmp_gt_f32_e32 vcc, s13, v6
	v_mul_f32_e32 v62, 0x4b800000, v6
	s_nop 0
	v_cndmask_b32_e32 v6, v6, v62, vcc
	v_rsq_f32_e32 v6, v6
	s_nop 0
	v_mul_f32_e32 v62, 0x45800000, v6
	v_cndmask_b32_e32 v6, v6, v62, vcc
	v_mul_f32_e32 v62, v7, v6
	v_xor_b32_e32 v6, v66, v67
	v_ashrrev_i32_e32 v6, 31, v6
	v_ffbh_i32_e32 v7, v67
	v_add_u32_e32 v6, 32, v6
	v_add_u32_e32 v7, -1, v7
	v_min_u32_e32 v63, v7, v6
	v_lshlrev_b64 v[6:7], v63, v[66:67]
	v_min_u32_e32 v6, 1, v6
	v_or_b32_e32 v6, v7, v6
	v_cvt_f32_i32_e32 v6, v6
	v_sub_u32_e32 v7, 32, v63
	v_ldexp_f32 v6, v6, v7
	v_mul_f32_e32 v6, 0x35800000, v6
	v_fmamk_f32 v6, v6, 0x3a800000, v222
	v_cmp_gt_f32_e32 vcc, s13, v6
	v_mul_f32_e32 v7, 0x4b800000, v6
	s_nop 0
	v_cndmask_b32_e32 v6, v6, v7, vcc
	v_rsq_f32_e32 v6, v6
	s_nop 0
	v_mul_f32_e32 v7, 0x45800000, v6
	v_cndmask_b32_e32 v6, v6, v7, vcc
	v_mul_f32_e32 v63, v64, v6
	v_xor_b32_e32 v6, v58, v59
	v_ashrrev_i32_e32 v6, 31, v6
	v_ffbh_i32_e32 v7, v59
	v_add_u32_e32 v6, 32, v6
	v_add_u32_e32 v7, -1, v7
	v_min_u32_e32 v64, v7, v6
	v_lshlrev_b64 v[6:7], v64, v[58:59]
	v_min_u32_e32 v6, 1, v6
	v_or_b32_e32 v6, v7, v6
	v_cvt_f32_i32_e32 v6, v6
	v_sub_u32_e32 v7, 32, v64
	v_ldexp_f32 v6, v6, v7
	v_mul_f32_e32 v6, 0x35800000, v6
	v_fmamk_f32 v6, v6, 0x3a800000, v222
	v_cmp_gt_f32_e32 vcc, s13, v6
	v_mul_f32_e32 v7, 0x4b800000, v6
	s_nop 0
	v_cndmask_b32_e32 v6, v6, v7, vcc
	v_rsq_f32_e32 v6, v6
	s_nop 0
	v_mul_f32_e32 v7, 0x45800000, v6
	v_cndmask_b32_e32 v6, v6, v7, vcc
	v_mul_f32_e32 v58, v8, v6
	v_xor_b32_e32 v6, v68, v69
	v_ashrrev_i32_e32 v6, 31, v6
	v_ffbh_i32_e32 v7, v69
	v_add_u32_e32 v6, 32, v6
	v_add_u32_e32 v7, -1, v7
	v_min_u32_e32 v8, v7, v6
	v_lshlrev_b64 v[6:7], v8, v[68:69]
	v_min_u32_e32 v6, 1, v6
	v_or_b32_e32 v6, v7, v6
	v_cvt_f32_i32_e32 v6, v6
	v_sub_u32_e32 v7, 32, v8
	v_ldexp_f32 v6, v6, v7
	v_mul_f32_e32 v6, 0x35800000, v6
	v_fmamk_f32 v6, v6, 0x3a800000, v222
	v_cmp_gt_f32_e32 vcc, s13, v6
	v_mul_f32_e32 v7, 0x4b800000, v6
	s_nop 0
	v_cndmask_b32_e32 v6, v6, v7, vcc
	v_rsq_f32_e32 v6, v6
	s_nop 0
	v_mul_f32_e32 v7, 0x45800000, v6
	v_cndmask_b32_e32 v6, v6, v7, vcc
	v_mul_f32_e32 v8, v65, v6
	v_xor_b32_e32 v6, v60, v61
	v_ashrrev_i32_e32 v6, 31, v6
	v_ffbh_i32_e32 v7, v61
	v_add_u32_e32 v6, 32, v6
	v_add_u32_e32 v7, -1, v7
	v_min_u32_e32 v59, v7, v6
	v_lshlrev_b64 v[6:7], v59, v[60:61]
	v_min_u32_e32 v6, 1, v6
	v_or_b32_e32 v6, v7, v6
	v_cvt_f32_i32_e32 v6, v6
	v_sub_u32_e32 v7, 32, v59
	v_ldexp_f32 v6, v6, v7
	v_mul_f32_e32 v6, 0x35800000, v6
	v_fmamk_f32 v6, v6, 0x3a800000, v222
	v_cmp_gt_f32_e32 vcc, s13, v6
	v_mul_f32_e32 v7, 0x4b800000, v6
	s_nop 0
	v_cndmask_b32_e32 v6, v6, v7, vcc
	v_rsq_f32_e32 v6, v6
	s_nop 0
	v_mul_f32_e32 v7, 0x45800000, v6
	v_cndmask_b32_e32 v6, v6, v7, vcc
	v_mul_f32_e32 v9, v9, v6
	v_cvt_pk_bf16_f32 v6, v0, v70
	s_waitcnt vmcnt(15)
; __device__ __forceinline__ unsigned cvt_pk_bf16(float lo, float hi) { unsigned r; asm volatile("v_cvt_pk_bf16_f32 %0, %1, %2" : "=v"(r) : "v"(lo), "v"(hi)); return r; }
; __device__ __forceinline__ void sg_task(const bf16* Z, bf16* YC, const ss_t* ssV, const float* vgain, const float* sw, const float* sb, LAS unsigned char* tile, int task, int tid) {
;     ...
;     for (int kk = 0; kk < 4; ++kk) {
;         float a[8];
; #pragma unroll
;         for (int e = 0; e < 4; ++e) { a[e] = w0[kk][e] * rsqrtf((float)(long long)sq[kk][e] * (1.0f / 1048576.0f) * (1.0f / 1024.0f) + EPS);
;                                       a[4 + e] = w1[kk][e] * rsqrtf((float)(long long)sq[kk][4 + e] * (1.0f / 1048576.0f) * (1.0f / 1024.0f) + EPS); }
;         u32x4 w; w.x = cvt_pk_bf16(a[0], a[1]); w.y = cvt_pk_bf16(a[2], a[3]); w.z = cvt_pk_bf16(a[4], a[5]); w.w = cvt_pk_bf16(a[6], a[7]);
;         bfrag[kk] = __builtin_bit_cast(bf16x8, w);
	v_xor_b32_e32 v0, v54, v55
	v_cvt_pk_bf16_f32 v7, v63, v8
	v_cvt_pk_bf16_f32 v8, v74, v62
	v_cvt_pk_bf16_f32 v9, v58, v9
	v_ashrrev_i32_e32 v0, 31, v0
	v_ffbh_i32_e32 v58, v55
	v_add_u32_e32 v0, 32, v0
	v_add_u32_e32 v58, -1, v58
	v_min_u32_e32 v0, v58, v0
	v_lshlrev_b64 v[54:55], v0, v[54:55]
	v_min_u32_e32 v54, 1, v54
	v_or_b32_e32 v54, v55, v54
	v_cvt_f32_i32_e32 v54, v54
	v_sub_u32_e32 v0, 32, v0
	v_ldexp_f32 v0, v54, v0
	v_mul_f32_e32 v0, 0x35800000, v0
	v_fmamk_f32 v0, v0, 0x3a800000, v222
	v_cmp_gt_f32_e32 vcc, s13, v0
	v_mul_f32_e32 v54, 0x4b800000, v0
	s_nop 0
	v_cndmask_b32_e32 v0, v0, v54, vcc
	v_rsq_f32_e32 v0, v0
	s_nop 0
	v_mul_f32_e32 v54, 0x45800000, v0
	v_cndmask_b32_e32 v0, v0, v54, vcc
	v_mul_f32_e32 v0, v42, v0
	v_xor_b32_e32 v42, v50, v51
	v_ashrrev_i32_e32 v42, 31, v42
	v_ffbh_i32_e32 v54, v51
	v_add_u32_e32 v42, 32, v42
	v_add_u32_e32 v54, -1, v54
	v_min_u32_e32 v42, v54, v42
	v_lshlrev_b64 v[50:51], v42, v[50:51]
	v_min_u32_e32 v50, 1, v50
	v_or_b32_e32 v50, v51, v50
	v_cvt_f32_i32_e32 v50, v50
	v_sub_u32_e32 v42, 32, v42
	v_ldexp_f32 v42, v50, v42
	v_mul_f32_e32 v42, 0x35800000, v42
	v_fmamk_f32 v42, v42, 0x3a800000, v222
	v_cmp_gt_f32_e32 vcc, s13, v42
	v_mul_f32_e32 v50, 0x4b800000, v42
	s_nop 0
	v_cndmask_b32_e32 v42, v42, v50, vcc
	v_rsq_f32_e32 v42, v42
	s_nop 0
	v_mul_f32_e32 v50, 0x45800000, v42
	v_cndmask_b32_e32 v42, v42, v50, vcc
	v_mul_f32_e32 v54, v10, v42
	v_xor_b32_e32 v10, v56, v57
	v_ashrrev_i32_e32 v10, 31, v10
	v_ffbh_i32_e32 v42, v57
	v_add_u32_e32 v10, 32, v10
	v_add_u32_e32 v42, -1, v42
	v_min_u32_e32 v10, v42, v10
	v_lshlrev_b64 v[50:51], v10, v[56:57]
	v_min_u32_e32 v42, 1, v50
	v_or_b32_e32 v42, v51, v42
	v_cvt_f32_i32_e32 v42, v42
	v_sub_u32_e32 v10, 32, v10
	v_ldexp_f32 v10, v42, v10
	v_mul_f32_e32 v10, 0x35800000, v10
	v_fmamk_f32 v10, v10, 0x3a800000, v222
	v_cmp_gt_f32_e32 vcc, s13, v10
	v_mul_f32_e32 v42, 0x4b800000, v10
	s_nop 0
	v_cndmask_b32_e32 v10, v10, v42, vcc
	v_rsq_f32_e32 v10, v10
	s_nop 0
	v_mul_f32_e32 v42, 0x45800000, v10
	v_cndmask_b32_e32 v10, v10, v42, vcc
	v_mul_f32_e32 v50, v43, v10
	v_xor_b32_e32 v10, v52, v53
	v_ashrrev_i32_e32 v10, 31, v10
	v_ffbh_i32_e32 v42, v53
	v_add_u32_e32 v10, 32, v10
	v_add_u32_e32 v42, -1, v42
	v_min_u32_e32 v10, v42, v10
	v_lshlrev_b64 v[42:43], v10, v[52:53]
	v_min_u32_e32 v42, 1, v42
	v_or_b32_e32 v42, v43, v42
	v_cvt_f32_i32_e32 v42, v42
	v_sub_u32_e32 v10, 32, v10
	v_ldexp_f32 v10, v42, v10
	v_mul_f32_e32 v10, 0x35800000, v10
	v_fmamk_f32 v10, v10, 0x3a800000, v222
	v_cmp_gt_f32_e32 vcc, s13, v10
	v_mul_f32_e32 v42, 0x4b800000, v10
	s_nop 0
	v_cndmask_b32_e32 v10, v10, v42, vcc
	v_rsq_f32_e32 v10, v10
	s_nop 0
	v_mul_f32_e32 v42, 0x45800000, v10
	v_cndmask_b32_e32 v10, v10, v42, vcc
	v_mul_f32_e32 v42, v11, v10
	v_xor_b32_e32 v10, v46, v47
	v_ashrrev_i32_e32 v10, 31, v10
	v_ffbh_i32_e32 v11, v47
	v_add_u32_e32 v10, 32, v10
	v_add_u32_e32 v11, -1, v11
	v_min_u32_e32 v43, v11, v10
	v_lshlrev_b64 v[10:11], v43, v[46:47]
	v_min_u32_e32 v10, 1, v10
	v_or_b32_e32 v10, v11, v10
	v_cvt_f32_i32_e32 v10, v10
	v_sub_u32_e32 v11, 32, v43
	v_ldexp_f32 v10, v10, v11
	v_mul_f32_e32 v10, 0x35800000, v10
	v_fmamk_f32 v10, v10, 0x3a800000, v222
	v_cmp_gt_f32_e32 vcc, s13, v10
	v_mul_f32_e32 v11, 0x4b800000, v10
	s_nop 0
	v_cndmask_b32_e32 v10, v10, v11, vcc
	v_rsq_f32_e32 v10, v10
	s_nop 0
	v_mul_f32_e32 v11, 0x45800000, v10
	v_cndmask_b32_e32 v10, v10, v11, vcc
	v_mul_f32_e32 v43, v44, v10
	v_xor_b32_e32 v10, v38, v39
	v_ashrrev_i32_e32 v10, 31, v10
	v_ffbh_i32_e32 v11, v39
	v_add_u32_e32 v10, 32, v10
	v_add_u32_e32 v11, -1, v11
	v_min_u32_e32 v44, v11, v10
	v_lshlrev_b64 v[10:11], v44, v[38:39]
	v_min_u32_e32 v10, 1, v10
	v_or_b32_e32 v10, v11, v10
	v_cvt_f32_i32_e32 v10, v10
	v_sub_u32_e32 v11, 32, v44
	v_ldexp_f32 v10, v10, v11
	v_mul_f32_e32 v10, 0x35800000, v10
	v_fmamk_f32 v10, v10, 0x3a800000, v222
	v_cmp_gt_f32_e32 vcc, s13, v10
	v_mul_f32_e32 v11, 0x4b800000, v10
	s_nop 0
	v_cndmask_b32_e32 v10, v10, v11, vcc
	v_rsq_f32_e32 v10, v10
	s_nop 0
	v_mul_f32_e32 v11, 0x45800000, v10
	v_cndmask_b32_e32 v10, v10, v11, vcc
	v_mul_f32_e32 v38, v12, v10
	v_xor_b32_e32 v10, v48, v49
	v_ashrrev_i32_e32 v10, 31, v10
	v_ffbh_i32_e32 v11, v49
	v_add_u32_e32 v10, 32, v10
	v_add_u32_e32 v11, -1, v11
	v_min_u32_e32 v12, v11, v10
	v_lshlrev_b64 v[10:11], v12, v[48:49]
	v_min_u32_e32 v10, 1, v10
	v_or_b32_e32 v10, v11, v10
	v_cvt_f32_i32_e32 v10, v10
	v_sub_u32_e32 v11, 32, v12
	v_ldexp_f32 v10, v10, v11
	v_mul_f32_e32 v10, 0x35800000, v10
	v_fmamk_f32 v10, v10, 0x3a800000, v222
	v_cmp_gt_f32_e32 vcc, s13, v10
	v_mul_f32_e32 v11, 0x4b800000, v10
	s_nop 0
	v_cndmask_b32_e32 v10, v10, v11, vcc
	v_rsq_f32_e32 v10, v10
	s_nop 0
	v_mul_f32_e32 v11, 0x45800000, v10
	v_cndmask_b32_e32 v10, v10, v11, vcc
	v_mul_f32_e32 v12, v45, v10
	v_xor_b32_e32 v10, v40, v41
	v_ashrrev_i32_e32 v10, 31, v10
	v_ffbh_i32_e32 v11, v41
	v_add_u32_e32 v10, 32, v10
	v_add_u32_e32 v11, -1, v11
	v_min_u32_e32 v39, v11, v10
	v_lshlrev_b64 v[10:11], v39, v[40:41]
	v_min_u32_e32 v10, 1, v10
	v_or_b32_e32 v10, v11, v10
	v_cvt_f32_i32_e32 v10, v10
	v_sub_u32_e32 v11, 32, v39
	v_ldexp_f32 v10, v10, v11
	v_mul_f32_e32 v10, 0x35800000, v10
	v_fmamk_f32 v10, v10, 0x3a800000, v222
	v_cmp_gt_f32_e32 vcc, s13, v10
	v_mul_f32_e32 v11, 0x4b800000, v10
	s_nop 0
	v_cndmask_b32_e32 v10, v10, v11, vcc
	v_rsq_f32_e32 v10, v10
	s_nop 0
	v_mul_f32_e32 v11, 0x45800000, v10
	v_cndmask_b32_e32 v10, v10, v11, vcc
	v_mul_f32_e32 v13, v13, v10
	v_cvt_pk_bf16_f32 v10, v0, v50
	s_waitcnt vmcnt(9)
; __device__ __forceinline__ unsigned cvt_pk_bf16(float lo, float hi) { unsigned r; asm volatile("v_cvt_pk_bf16_f32 %0, %1, %2" : "=v"(r) : "v"(lo), "v"(hi)); return r; }
; __device__ __forceinline__ unsigned tr_addr16(unsigned lane, unsigned c, unsigned ks, unsigned t) {
;     const unsigned g = lane >> 4, q = (lane & 15) >> 2, p = lane & 3;
;     return off_b(32 * ks + 8 * g + 4 * t + q, 2 * c + (p >> 1)) + 8 * (p & 1);
; }
; __device__ __forceinline__ void sg_task(const bf16* Z, bf16* YC, const ss_t* ssV, const float* vgain, const float* sw, const float* sb, LAS unsigned char* tile, int task, int tid) {
;     ...
;     for (int kk = 0; kk < 4; ++kk) {
;         float a[8];
; #pragma unroll
;         for (int e = 0; e < 4; ++e) { a[e] = w0[kk][e] * rsqrtf((float)(long long)sq[kk][e] * (1.0f / 1048576.0f) * (1.0f / 1024.0f) + EPS);
;                                       a[4 + e] = w1[kk][e] * rsqrtf((float)(long long)sq[kk][4 + e] * (1.0f / 1048576.0f) * (1.0f / 1024.0f) + EPS); }
;         u32x4 w; w.x = cvt_pk_bf16(a[0], a[1]); w.y = cvt_pk_bf16(a[2], a[3]); w.z = cvt_pk_bf16(a[4], a[5]); w.w = cvt_pk_bf16(a[6], a[7]);
;         bfrag[kk] = __builtin_bit_cast(bf16x8, w);
;     }
;     __syncthreads();
	v_xor_b32_e32 v0, v34, v35
	v_cvt_pk_bf16_f32 v11, v43, v12
	v_cvt_pk_bf16_f32 v12, v54, v42
	v_cvt_pk_bf16_f32 v13, v38, v13
	v_ashrrev_i32_e32 v0, 31, v0
	v_ffbh_i32_e32 v38, v35
	v_add_u32_e32 v0, 32, v0
	v_add_u32_e32 v38, -1, v38
	v_min_u32_e32 v0, v38, v0
	v_lshlrev_b64 v[34:35], v0, v[34:35]
	v_min_u32_e32 v34, 1, v34
	v_or_b32_e32 v34, v35, v34
	v_cvt_f32_i32_e32 v34, v34
	v_sub_u32_e32 v0, 32, v0
	v_lshl_or_b32 v43, v124, 2, s2
	v_ldexp_f32 v0, v34, v0
	v_mul_f32_e32 v0, 0x35800000, v0
	v_fmamk_f32 v0, v0, 0x3a800000, v222
	v_cmp_gt_f32_e32 vcc, s13, v0
	v_mul_f32_e32 v34, 0x4b800000, v0
	s_nop 0
	v_cndmask_b32_e32 v0, v0, v34, vcc
	v_rsq_f32_e32 v0, v0
	s_nop 0
	v_mul_f32_e32 v34, 0x45800000, v0
	v_cndmask_b32_e32 v0, v0, v34, vcc
	v_mul_f32_e32 v0, v22, v0
	v_xor_b32_e32 v22, v30, v31
	v_ashrrev_i32_e32 v22, 31, v22
	v_ffbh_i32_e32 v34, v31
	v_add_u32_e32 v22, 32, v22
	v_add_u32_e32 v34, -1, v34
	v_min_u32_e32 v22, v34, v22
	v_lshlrev_b64 v[30:31], v22, v[30:31]
	v_min_u32_e32 v30, 1, v30
	v_or_b32_e32 v30, v31, v30
	v_cvt_f32_i32_e32 v30, v30
	v_sub_u32_e32 v22, 32, v22
	v_ldexp_f32 v22, v30, v22
	v_mul_f32_e32 v22, 0x35800000, v22
	v_fmamk_f32 v22, v22, 0x3a800000, v222
	v_cmp_gt_f32_e32 vcc, s13, v22
	v_mul_f32_e32 v30, 0x4b800000, v22
	s_nop 0
	v_cndmask_b32_e32 v22, v22, v30, vcc
	v_rsq_f32_e32 v22, v22
	s_nop 0
	v_mul_f32_e32 v30, 0x45800000, v22
	v_cndmask_b32_e32 v22, v22, v30, vcc
	v_mul_f32_e32 v34, v14, v22
	v_xor_b32_e32 v14, v36, v37
	v_ashrrev_i32_e32 v14, 31, v14
	v_ffbh_i32_e32 v22, v37
	v_add_u32_e32 v14, 32, v14
	v_add_u32_e32 v22, -1, v22
	v_min_u32_e32 v14, v22, v14
	v_lshlrev_b64 v[30:31], v14, v[36:37]
	v_min_u32_e32 v22, 1, v30
	v_or_b32_e32 v22, v31, v22
	v_cvt_f32_i32_e32 v22, v22
	v_sub_u32_e32 v14, 32, v14
	v_ldexp_f32 v14, v22, v14
	v_mul_f32_e32 v14, 0x35800000, v14
	v_fmamk_f32 v14, v14, 0x3a800000, v222
	v_cmp_gt_f32_e32 vcc, s13, v14
	v_mul_f32_e32 v22, 0x4b800000, v14
	s_nop 0
	v_cndmask_b32_e32 v14, v14, v22, vcc
	v_rsq_f32_e32 v14, v14
	s_nop 0
	v_mul_f32_e32 v22, 0x45800000, v14
	v_cndmask_b32_e32 v14, v14, v22, vcc
	v_mul_f32_e32 v30, v23, v14
	v_xor_b32_e32 v14, v32, v33
	v_ashrrev_i32_e32 v14, 31, v14
	v_ffbh_i32_e32 v22, v33
	v_add_u32_e32 v14, 32, v14
	v_add_u32_e32 v22, -1, v22
	v_min_u32_e32 v14, v22, v14
	v_lshlrev_b64 v[22:23], v14, v[32:33]
	v_min_u32_e32 v22, 1, v22
	v_or_b32_e32 v22, v23, v22
	v_cvt_f32_i32_e32 v22, v22
	v_sub_u32_e32 v14, 32, v14
	v_ldexp_f32 v14, v22, v14
	v_mul_f32_e32 v14, 0x35800000, v14
	v_fmamk_f32 v14, v14, 0x3a800000, v222
	v_cmp_gt_f32_e32 vcc, s13, v14
	v_mul_f32_e32 v22, 0x4b800000, v14
	s_nop 0
	v_cndmask_b32_e32 v14, v14, v22, vcc
	v_rsq_f32_e32 v14, v14
	s_nop 0
	v_mul_f32_e32 v22, 0x45800000, v14
	v_cndmask_b32_e32 v14, v14, v22, vcc
	v_mul_f32_e32 v22, v15, v14
	v_xor_b32_e32 v14, v26, v27
	v_ashrrev_i32_e32 v14, 31, v14
	v_ffbh_i32_e32 v15, v27
	v_add_u32_e32 v14, 32, v14
	v_add_u32_e32 v15, -1, v15
	v_min_u32_e32 v23, v15, v14
	v_lshlrev_b64 v[14:15], v23, v[26:27]
	v_min_u32_e32 v14, 1, v14
	v_or_b32_e32 v14, v15, v14
	v_cvt_f32_i32_e32 v14, v14
	v_sub_u32_e32 v15, 32, v23
	v_ldexp_f32 v14, v14, v15
	v_mul_f32_e32 v14, 0x35800000, v14
	v_fmamk_f32 v14, v14, 0x3a800000, v222
	v_cmp_gt_f32_e32 vcc, s13, v14
	v_mul_f32_e32 v15, 0x4b800000, v14
	s_nop 0
	v_cndmask_b32_e32 v14, v14, v15, vcc
	v_rsq_f32_e32 v14, v14
	s_nop 0
	v_mul_f32_e32 v15, 0x45800000, v14
	v_cndmask_b32_e32 v14, v14, v15, vcc
	v_mul_f32_e32 v23, v24, v14
	v_xor_b32_e32 v14, v18, v19
	v_ashrrev_i32_e32 v14, 31, v14
	v_ffbh_i32_e32 v15, v19
	v_add_u32_e32 v14, 32, v14
	v_add_u32_e32 v15, -1, v15
	v_min_u32_e32 v24, v15, v14
	v_lshlrev_b64 v[14:15], v24, v[18:19]
	v_min_u32_e32 v14, 1, v14
	v_or_b32_e32 v14, v15, v14
	v_cvt_f32_i32_e32 v14, v14
	v_sub_u32_e32 v15, 32, v24
	v_ldexp_f32 v14, v14, v15
	v_mul_f32_e32 v14, 0x35800000, v14
	v_fmamk_f32 v14, v14, 0x3a800000, v222
	v_cmp_gt_f32_e32 vcc, s13, v14
	v_mul_f32_e32 v15, 0x4b800000, v14
	s_nop 0
	v_cndmask_b32_e32 v14, v14, v15, vcc
	v_rsq_f32_e32 v14, v14
	s_nop 0
	v_mul_f32_e32 v15, 0x45800000, v14
	v_cndmask_b32_e32 v14, v14, v15, vcc
	v_mul_f32_e32 v18, v16, v14
	v_xor_b32_e32 v14, v28, v29
	v_ashrrev_i32_e32 v14, 31, v14
	v_ffbh_i32_e32 v15, v29
	v_add_u32_e32 v14, 32, v14
	v_add_u32_e32 v15, -1, v15
	v_min_u32_e32 v16, v15, v14
	v_lshlrev_b64 v[14:15], v16, v[28:29]
	v_min_u32_e32 v14, 1, v14
	v_or_b32_e32 v14, v15, v14
	v_cvt_f32_i32_e32 v14, v14
	v_sub_u32_e32 v15, 32, v16
	v_and_b32_e32 v28, 12, v123
	v_and_b32_e32 v29, 8, v122
	v_ldexp_f32 v14, v14, v15
	v_mul_f32_e32 v14, 0x35800000, v14
	v_fmamk_f32 v14, v14, 0x3a800000, v222
	v_cmp_gt_f32_e32 vcc, s13, v14
	v_mul_f32_e32 v15, 0x4b800000, v14
	v_add_u32_e32 v31, 0, v29
	v_cndmask_b32_e32 v14, v14, v15, vcc
	v_rsq_f32_e32 v14, v14
	s_nop 0
	v_mul_f32_e32 v15, 0x45800000, v14
	v_cndmask_b32_e32 v14, v14, v15, vcc
	v_mul_f32_e32 v16, v25, v14
	v_xor_b32_e32 v14, v20, v21
	v_ashrrev_i32_e32 v14, 31, v14
	v_ffbh_i32_e32 v15, v21
	v_add_u32_e32 v14, 32, v14
	v_add_u32_e32 v15, -1, v15
	v_min_u32_e32 v19, v15, v14
	v_lshlrev_b64 v[14:15], v19, v[20:21]
	v_min_u32_e32 v14, 1, v14
	v_or_b32_e32 v14, v15, v14
	v_cvt_f32_i32_e32 v14, v14
	v_sub_u32_e32 v15, 32, v19
	v_ldexp_f32 v14, v14, v15
	v_mul_f32_e32 v14, 0x35800000, v14
	v_fmamk_f32 v14, v14, 0x3a800000, v222
	v_cmp_gt_f32_e32 vcc, s13, v14
	v_mul_f32_e32 v15, 0x4b800000, v14
	s_nop 0
	v_cndmask_b32_e32 v14, v14, v15, vcc
	v_rsq_f32_e32 v14, v14
	s_nop 0
	v_mul_f32_e32 v15, 0x45800000, v14
	v_cndmask_b32_e32 v14, v14, v15, vcc
	v_mul_f32_e32 v17, v17, v14
	v_cvt_pk_bf16_f32 v14, v0, v30
	v_cvt_pk_bf16_f32 v15, v23, v16
	v_cvt_pk_bf16_f32 v16, v34, v22
	v_cvt_pk_bf16_f32 v17, v18, v17
	v_bfe_u32 v18, v123, 1, 5
	v_and_b32_e32 v33, 24, v18
	v_bfe_u32 v0, v123, 2, 2
	v_lshrrev_b32_e32 v18, 3, v123
	v_or_b32_e32 v22, 4, v33
	v_bfe_u32 v30, v125, 1, 1
	v_and_or_b32 v32, v18, 2, v28
	v_or_b32_e32 v20, v33, v0
	v_bfe_u32 v36, v22, 2, 2
	v_lshlrev_b32_e32 v34, 8, v20
	v_or_b32_e32 v20, v30, v32
	v_or_b32_e32 v23, v22, v0
	v_bitop3_b32 v22, v36, v30, v28 bitop3:0x36
	v_lshlrev_b32_e32 v20, 4, v20
	v_lshlrev_b32_e32 v35, 8, v23
	v_lshl_add_u32 v22, v22, 4, 0
	v_add3_u32 v39, v31, v20, v34
	v_add3_u32 v22, v22, v35, v29
	v_or_b32_e32 v26, 36, v33
	s_waitcnt lgkmcnt(0)
	s_barrier
; __device__ __forceinline__ unsigned cvt_pk_bf16(float lo, float hi) { unsigned r; asm volatile("v_cvt_pk_bf16_f32 %0, %1, %2" : "=v"(r) : "v"(lo), "v"(hi)); return r; }
; __device__ __forceinline__ float bf_lo(unsigned u) { return __uint_as_float(u << 16); }
; __device__ __forceinline__ float bf_hi(unsigned u) { return __uint_as_float(u & 0xffff0000u); }
; __device__ __forceinline__ s16x4 vtr(const LAS unsigned char* p) { return __builtin_bit_cast(s16x4, __builtin_amdgcn_ds_read_tr16_b64_v4i16((LAS s16x4*)p)); }
; __device__ __forceinline__ bf16x8 cat4(s16x4 a, s16x4 b) { return __builtin_shufflevector(a, b, 0, 1, 2, 3, 4, 5, 6, 7); }
; __device__ __forceinline__ void sg_task(const bf16* Z, bf16* YC, const ss_t* ssV, const float* vgain, const float* sw, const float* sb, LAS unsigned char* tile, int task, int tid) {
;     ...
;     for (int cb = 0; cb < 8; ++cb) {
;         f32x4 acc = {0.f, 0.f, 0.f, 0.f};
; #pragma unroll
;         for (int kk = 0; kk < 4; ++kk) { const s16x4 v0 = vtr(tile + tr_addr16(lane, cb, kk, 0)), v1 = vtr(tile + tr_addr16(lane, cb, kk, 1));
;             acc = __builtin_amdgcn_mfma_f32_16x16x32_bf16(cat4(v0, v1), bfrag[kk], acc, 0, 0, 0); }
;         const int c0 = g * 128 + cb * 16 + fq * 4;
;         const f32x4 gn = *(const f32x4*)(vgain + c0);
;         u32x2 w; w.x = cvt_pk_bf16(bf_lo(uu[cb].x) * (acc[0] * gn[0] + bias), bf_hi(uu[cb].x) * (acc[1] * gn[1] + bias));
;         w.y = cvt_pk_bf16(bf_lo(uu[cb].y) * (acc[2] * gn[2] + bias), bf_hi(uu[cb].y) * (acc[3] * gn[3] + bias));
;         *(u32x2*)(YC + tokp * 2048 + 1024 + c0) = w;
	ds_read_b64_tr_b16 v[20:21], v39
	ds_read_b64_tr_b16 v[22:23], v22
	ds_read_b64_tr_b16 v[24:25], v39 offset:8192
	v_bfe_u32 v38, v26, 2, 2
	v_or_b32_e32 v27, v26, v0
	v_bitop3_b32 v26, v38, v30, v28 bitop3:0x36
	v_lshlrev_b32_e32 v37, 8, v27
	v_lshl_add_u32 v26, v26, 4, 0
	v_add3_u32 v26, v26, v37, v29
	ds_read_b64_tr_b16 v[26:27], v26
	s_waitcnt lgkmcnt(2)
	v_mfma_f32_16x16x32_bf16 v[20:23], v[20:23], v[2:5], 0
	v_lshlrev_b64 v[18:19], 12, v[116:117]
	v_lshl_add_u64 v[18:19], s[64:65], 0, v[18:19]
	s_waitcnt lgkmcnt(0)
	v_mfma_f32_16x16x32_bf16 v[20:23], v[24:27], v[6:9], v[20:23]
	v_or_b32_e32 v26, 0x44, v33
	v_bfe_u32 v41, v26, 2, 2
	v_or_b32_e32 v27, v26, v0
	v_bitop3_b32 v26, v41, v30, v28 bitop3:0x36
	v_lshlrev_b32_e32 v40, 8, v27
	v_lshl_add_u32 v26, v26, 4, 0
	v_add3_u32 v26, v26, v40, v29
	ds_read_b64_tr_b16 v[24:25], v39 offset:16384
	ds_read_b64_tr_b16 v[26:27], v26
	s_waitcnt lgkmcnt(0)
	v_mfma_f32_16x16x32_bf16 v[20:23], v[24:27], v[10:13], v[20:23]
	v_or_b32_e32 v26, 0x64, v33
	v_or_b32_e32 v0, v26, v0
	v_bfe_u32 v42, v26, 2, 2
	ds_read_b64_tr_b16 v[24:25], v39 offset:24576
	v_lshlrev_b32_e32 v39, 8, v0
	v_bitop3_b32 v0, v42, v30, v28 bitop3:0x36
	v_lshl_add_u32 v0, v0, 4, 0
	v_add3_u32 v0, v0, v39, v29
	ds_read_b64_tr_b16 v[26:27], v0
	v_lshlrev_b32_e32 v33, 2, v43
	s_waitcnt lgkmcnt(0)
	v_mfma_f32_16x16x32_bf16 v[20:23], v[24:27], v[14:17], v[20:23]
	global_load_dwordx4 v[24:27], v33, s[56:57]
	global_load_dwordx4 v[44:47], v33, s[56:57] offset:64
	global_load_dwordx4 v[48:51], v33, s[56:57] offset:128
	global_load_dwordx4 v[52:55], v33, s[56:57] offset:192
	global_load_dwordx4 v[56:59], v33, s[56:57] offset:256
	global_load_dwordx4 v[60:63], v33, s[56:57] offset:320
	global_load_dwordx4 v[64:67], v33, s[56:57] offset:384
	global_load_dwordx4 v[68:71], v33, s[56:57] offset:448
	s_waitcnt vmcnt(16)
	v_lshlrev_b32_e32 v0, 16, v118
	s_waitcnt vmcnt(0)
	s_nop 3
	v_fma_f32 v20, v20, v24, v120
	v_mul_f32_e32 v0, v20, v0
	v_and_b32_e32 v20, 0xffff0000, v118
	v_fma_f32 v21, v21, v25, v120
	v_mul_f32_e32 v20, v21, v20
	v_cvt_pk_bf16_f32 v20, v0, v20
	v_lshlrev_b32_e32 v0, 16, v119
	v_fma_f32 v21, v22, v26, v120
	v_mul_f32_e32 v0, v21, v0
	v_and_b32_e32 v21, 0xffff0000, v119
	v_fma_f32 v22, v23, v27, v120
	v_mul_f32_e32 v21, v22, v21
	v_cvt_pk_bf16_f32 v21, v0, v21
	v_lshlrev_b32_e32 v0, 1, v43
	v_lshl_add_u64 v[26:27], v[18:19], 0, v[0:1]
	v_or_b32_e32 v0, 2, v30
	global_store_dwordx2 v[26:27], v[20:21], off offset:2048
	v_bitop3_b32 v18, v30, v32, 2 bitop3:0x36
	v_bitop3_b32 v20, v36, v0, v28 bitop3:0x36
	v_lshlrev_b32_e32 v18, 4, v18
	v_lshl_add_u32 v20, v20, 4, 0
	v_add3_u32 v43, v31, v18, v34
	v_add3_u32 v20, v20, v35, v29
	ds_read_b64_tr_b16 v[18:19], v43
	ds_read_b64_tr_b16 v[20:21], v20
	ds_read_b64_tr_b16 v[22:23], v43 offset:8192
	v_bitop3_b32 v24, v38, v0, v28 bitop3:0x36
	v_lshl_add_u32 v24, v24, 4, 0
	v_add3_u32 v24, v24, v37, v29
	ds_read_b64_tr_b16 v[24:25], v24
	s_waitcnt lgkmcnt(2)
	v_mfma_f32_16x16x32_bf16 v[18:21], v[18:21], v[2:5], 0
	s_waitcnt lgkmcnt(0)
	v_mfma_f32_16x16x32_bf16 v[18:21], v[22:25], v[6:9], v[18:21]
	v_bitop3_b32 v24, v41, v0, v28 bitop3:0x36
	v_lshl_add_u32 v24, v24, 4, 0
	v_add3_u32 v24, v24, v40, v29
	ds_read_b64_tr_b16 v[22:23], v43 offset:16384
	ds_read_b64_tr_b16 v[24:25], v24
	v_bitop3_b32 v0, v42, v0, v28 bitop3:0x36
	v_lshl_add_u32 v0, v0, 4, 0
	v_add3_u32 v0, v0, v39, v29
	s_waitcnt lgkmcnt(0)
	v_mfma_f32_16x16x32_bf16 v[18:21], v[22:25], v[10:13], v[18:21]
	ds_read_b64_tr_b16 v[22:23], v43 offset:24576
	ds_read_b64_tr_b16 v[24:25], v0
	v_lshlrev_b32_e32 v0, 16, v114
	s_waitcnt lgkmcnt(0)
	v_mfma_f32_16x16x32_bf16 v[18:21], v[22:25], v[14:17], v[18:21]
	v_mov_b32_e32 v22, v44
	v_mov_b32_e32 v23, v45
	v_mov_b32_e32 v24, v46
	v_mov_b32_e32 v25, v47
	s_nop 5
	v_fma_f32 v18, v18, v22, v120
	v_mul_f32_e32 v0, v18, v0
	v_and_b32_e32 v18, 0xffff0000, v114
	v_fma_f32 v19, v19, v23, v120
	v_mul_f32_e32 v18, v19, v18
	v_cvt_pk_bf16_f32 v18, v0, v18
	v_lshlrev_b32_e32 v0, 16, v115
	v_fma_f32 v19, v20, v24, v120
	v_mul_f32_e32 v0, v19, v0
	v_and_b32_e32 v19, 0xffff0000, v115
	v_fma_f32 v20, v21, v25, v120
	v_mul_f32_e32 v19, v20, v19
	v_cvt_pk_bf16_f32 v19, v0, v19
	v_or_b32_e32 v0, 4, v30
	global_store_dwordx2 v[26:27], v[18:19], off offset:2080
	v_bitop3_b32 v18, v30, v32, 4 bitop3:0x36
	v_bitop3_b32 v20, v36, v0, v28 bitop3:0x36
	v_lshlrev_b32_e32 v18, 4, v18
	v_lshl_add_u32 v20, v20, 4, 0
	v_add3_u32 v43, v31, v18, v34
	v_add3_u32 v20, v20, v35, v29
	ds_read_b64_tr_b16 v[18:19], v43
	ds_read_b64_tr_b16 v[20:21], v20
	ds_read_b64_tr_b16 v[22:23], v43 offset:8192
	v_bitop3_b32 v24, v38, v0, v28 bitop3:0x36
	v_lshl_add_u32 v24, v24, 4, 0
	v_add3_u32 v24, v24, v37, v29
	ds_read_b64_tr_b16 v[24:25], v24
	s_waitcnt lgkmcnt(2)
	v_mfma_f32_16x16x32_bf16 v[18:21], v[18:21], v[2:5], 0
	s_waitcnt lgkmcnt(0)
	v_mfma_f32_16x16x32_bf16 v[18:21], v[22:25], v[6:9], v[18:21]
	v_bitop3_b32 v24, v41, v0, v28 bitop3:0x36
	v_lshl_add_u32 v24, v24, 4, 0
	v_add3_u32 v24, v24, v40, v29
	ds_read_b64_tr_b16 v[22:23], v43 offset:16384
	ds_read_b64_tr_b16 v[24:25], v24
	v_bitop3_b32 v0, v42, v0, v28 bitop3:0x36
	v_lshl_add_u32 v0, v0, 4, 0
	v_add3_u32 v0, v0, v39, v29
	s_waitcnt lgkmcnt(0)
	v_mfma_f32_16x16x32_bf16 v[18:21], v[22:25], v[10:13], v[18:21]
	ds_read_b64_tr_b16 v[22:23], v43 offset:24576
	ds_read_b64_tr_b16 v[24:25], v0
	v_lshlrev_b32_e32 v0, 16, v112
	s_waitcnt lgkmcnt(0)
; __device__ __forceinline__ unsigned cvt_pk_bf16(float lo, float hi) { unsigned r; asm volatile("v_cvt_pk_bf16_f32 %0, %1, %2" : "=v"(r) : "v"(lo), "v"(hi)); return r; }
; __device__ __forceinline__ float bf_lo(unsigned u) { return __uint_as_float(u << 16); }
; __device__ __forceinline__ float bf_hi(unsigned u) { return __uint_as_float(u & 0xffff0000u); }
; __device__ __forceinline__ s16x4 vtr(const LAS unsigned char* p) { return __builtin_bit_cast(s16x4, __builtin_amdgcn_ds_read_tr16_b64_v4i16((LAS s16x4*)p)); }
; __device__ __forceinline__ bf16x8 cat4(s16x4 a, s16x4 b) { return __builtin_shufflevector(a, b, 0, 1, 2, 3, 4, 5, 6, 7); }
; __device__ __forceinline__ void sg_task(const bf16* Z, bf16* YC, const ss_t* ssV, const float* vgain, const float* sw, const float* sb, LAS unsigned char* tile, int task, int tid) {
;     ...
;     for (int cb = 0; cb < 8; ++cb) {
;         f32x4 acc = {0.f, 0.f, 0.f, 0.f};
; #pragma unroll
;         for (int kk = 0; kk < 4; ++kk) { const s16x4 v0 = vtr(tile + tr_addr16(lane, cb, kk, 0)), v1 = vtr(tile + tr_addr16(lane, cb, kk, 1));
;             acc = __builtin_amdgcn_mfma_f32_16x16x32_bf16(cat4(v0, v1), bfrag[kk], acc, 0, 0, 0); }
;         const int c0 = g * 128 + cb * 16 + fq * 4;
;         const f32x4 gn = *(const f32x4*)(vgain + c0);
;         u32x2 w; w.x = cvt_pk_bf16(bf_lo(uu[cb].x) * (acc[0] * gn[0] + bias), bf_hi(uu[cb].x) * (acc[1] * gn[1] + bias));
;         w.y = cvt_pk_bf16(bf_lo(uu[cb].y) * (acc[2] * gn[2] + bias), bf_hi(uu[cb].y) * (acc[3] * gn[3] + bias));
;         *(u32x2*)(YC + tokp * 2048 + 1024 + c0) = w;
	v_mfma_f32_16x16x32_bf16 v[18:21], v[22:25], v[14:17], v[18:21]
	v_mov_b32_e32 v22, v48
	v_mov_b32_e32 v23, v49
	v_mov_b32_e32 v24, v50
	v_mov_b32_e32 v25, v51
	s_nop 5
	v_fma_f32 v18, v18, v22, v120
	v_mul_f32_e32 v0, v18, v0
	v_and_b32_e32 v18, 0xffff0000, v112
	v_fma_f32 v19, v19, v23, v120
	v_mul_f32_e32 v18, v19, v18
	v_cvt_pk_bf16_f32 v18, v0, v18
	v_lshlrev_b32_e32 v0, 16, v113
	v_fma_f32 v19, v20, v24, v120
	v_mul_f32_e32 v0, v19, v0
	v_and_b32_e32 v19, 0xffff0000, v113
	v_fma_f32 v20, v21, v25, v120
	v_mul_f32_e32 v19, v20, v19
	v_cvt_pk_bf16_f32 v19, v0, v19
	v_or_b32_e32 v0, 6, v30
	global_store_dwordx2 v[26:27], v[18:19], off offset:2112
	v_bitop3_b32 v18, v30, v32, 6 bitop3:0x36
	v_bitop3_b32 v20, v36, v0, v28 bitop3:0x36
	v_lshlrev_b32_e32 v18, 4, v18
	v_lshl_add_u32 v20, v20, 4, 0
	v_add3_u32 v43, v31, v18, v34
	v_add3_u32 v20, v20, v35, v29
	ds_read_b64_tr_b16 v[18:19], v43
	ds_read_b64_tr_b16 v[20:21], v20
	ds_read_b64_tr_b16 v[22:23], v43 offset:8192
	v_bitop3_b32 v24, v38, v0, v28 bitop3:0x36
	v_lshl_add_u32 v24, v24, 4, 0
	v_add3_u32 v24, v24, v37, v29
	ds_read_b64_tr_b16 v[24:25], v24
	s_waitcnt lgkmcnt(2)
	v_mfma_f32_16x16x32_bf16 v[18:21], v[18:21], v[2:5], 0
	s_waitcnt lgkmcnt(0)
	v_mfma_f32_16x16x32_bf16 v[18:21], v[22:25], v[6:9], v[18:21]
	v_bitop3_b32 v24, v41, v0, v28 bitop3:0x36
	v_lshl_add_u32 v24, v24, 4, 0
	v_add3_u32 v24, v24, v40, v29
	ds_read_b64_tr_b16 v[22:23], v43 offset:16384
	ds_read_b64_tr_b16 v[24:25], v24
	v_bitop3_b32 v0, v42, v0, v28 bitop3:0x36
	v_lshl_add_u32 v0, v0, 4, 0
	v_add3_u32 v0, v0, v39, v29
	s_waitcnt lgkmcnt(0)
	v_mfma_f32_16x16x32_bf16 v[18:21], v[22:25], v[10:13], v[18:21]
	ds_read_b64_tr_b16 v[22:23], v43 offset:24576
	ds_read_b64_tr_b16 v[24:25], v0
	v_lshlrev_b32_e32 v0, 16, v110
	s_waitcnt lgkmcnt(0)
	v_mfma_f32_16x16x32_bf16 v[18:21], v[22:25], v[14:17], v[18:21]
	v_mov_b32_e32 v22, v52
	v_mov_b32_e32 v23, v53
	v_mov_b32_e32 v24, v54
	v_mov_b32_e32 v25, v55
	s_nop 5
	v_fma_f32 v18, v18, v22, v120
	v_mul_f32_e32 v0, v18, v0
	v_and_b32_e32 v18, 0xffff0000, v110
	v_fma_f32 v19, v19, v23, v120
	v_mul_f32_e32 v18, v19, v18
	v_cvt_pk_bf16_f32 v18, v0, v18
	v_lshlrev_b32_e32 v0, 16, v111
	v_fma_f32 v19, v20, v24, v120
	v_mul_f32_e32 v0, v19, v0
	v_and_b32_e32 v19, 0xffff0000, v111
	v_fma_f32 v20, v21, v25, v120
	v_mul_f32_e32 v19, v20, v19
	v_cvt_pk_bf16_f32 v19, v0, v19
	v_or_b32_e32 v0, 8, v30
	global_store_dwordx2 v[26:27], v[18:19], off offset:2144
	v_bitop3_b32 v18, v30, v32, 8 bitop3:0x36
	v_bitop3_b32 v20, v36, v0, v28 bitop3:0x36
	v_lshlrev_b32_e32 v18, 4, v18
	v_lshl_add_u32 v20, v20, 4, 0
	v_add3_u32 v43, v31, v18, v34
	v_add3_u32 v20, v20, v35, v29
	ds_read_b64_tr_b16 v[18:19], v43
	ds_read_b64_tr_b16 v[20:21], v20
	ds_read_b64_tr_b16 v[22:23], v43 offset:8192
	v_bitop3_b32 v24, v38, v0, v28 bitop3:0x36
	v_lshl_add_u32 v24, v24, 4, 0
	v_add3_u32 v24, v24, v37, v29
	ds_read_b64_tr_b16 v[24:25], v24
	s_waitcnt lgkmcnt(2)
	v_mfma_f32_16x16x32_bf16 v[18:21], v[18:21], v[2:5], 0
	s_waitcnt lgkmcnt(0)
	v_mfma_f32_16x16x32_bf16 v[18:21], v[22:25], v[6:9], v[18:21]
	v_bitop3_b32 v24, v41, v0, v28 bitop3:0x36
	v_lshl_add_u32 v24, v24, 4, 0
	v_add3_u32 v24, v24, v40, v29
	ds_read_b64_tr_b16 v[22:23], v43 offset:16384
	ds_read_b64_tr_b16 v[24:25], v24
	v_bitop3_b32 v0, v42, v0, v28 bitop3:0x36
	v_lshl_add_u32 v0, v0, 4, 0
	v_add3_u32 v0, v0, v39, v29
	s_waitcnt lgkmcnt(0)
	v_mfma_f32_16x16x32_bf16 v[18:21], v[22:25], v[10:13], v[18:21]
	ds_read_b64_tr_b16 v[22:23], v43 offset:24576
	ds_read_b64_tr_b16 v[24:25], v0
	v_lshlrev_b32_e32 v0, 16, v108
	s_waitcnt lgkmcnt(0)
	v_mfma_f32_16x16x32_bf16 v[18:21], v[22:25], v[14:17], v[18:21]
	v_mov_b32_e32 v22, v56
	v_mov_b32_e32 v23, v57
	v_mov_b32_e32 v24, v58
	v_mov_b32_e32 v25, v59
	s_nop 5
	v_fma_f32 v18, v18, v22, v120
	v_mul_f32_e32 v0, v18, v0
	v_and_b32_e32 v18, 0xffff0000, v108
	v_fma_f32 v19, v19, v23, v120
	v_mul_f32_e32 v18, v19, v18
	v_cvt_pk_bf16_f32 v18, v0, v18
	v_lshlrev_b32_e32 v0, 16, v109
	v_fma_f32 v19, v20, v24, v120
	v_mul_f32_e32 v0, v19, v0
	v_and_b32_e32 v19, 0xffff0000, v109
	v_fma_f32 v20, v21, v25, v120
	v_mul_f32_e32 v19, v20, v19
	v_cvt_pk_bf16_f32 v19, v0, v19
	v_or_b32_e32 v0, 10, v30
	global_store_dwordx2 v[26:27], v[18:19], off offset:2176
	v_bitop3_b32 v18, v30, v32, 10 bitop3:0x36
	v_bitop3_b32 v20, v36, v0, v28 bitop3:0x36
	v_lshlrev_b32_e32 v18, 4, v18
	v_lshl_add_u32 v20, v20, 4, 0
	v_add3_u32 v43, v31, v18, v34
	v_add3_u32 v20, v20, v35, v29
	ds_read_b64_tr_b16 v[18:19], v43
	ds_read_b64_tr_b16 v[20:21], v20
	ds_read_b64_tr_b16 v[22:23], v43 offset:8192
	v_bitop3_b32 v24, v38, v0, v28 bitop3:0x36
	v_lshl_add_u32 v24, v24, 4, 0
	v_add3_u32 v24, v24, v37, v29
	ds_read_b64_tr_b16 v[24:25], v24
	s_waitcnt lgkmcnt(2)
	v_mfma_f32_16x16x32_bf16 v[18:21], v[18:21], v[2:5], 0
	s_waitcnt lgkmcnt(0)
; __device__ __forceinline__ unsigned cvt_pk_bf16(float lo, float hi) { unsigned r; asm volatile("v_cvt_pk_bf16_f32 %0, %1, %2" : "=v"(r) : "v"(lo), "v"(hi)); return r; }
; __device__ __forceinline__ float bf_lo(unsigned u) { return __uint_as_float(u << 16); }
; __device__ __forceinline__ float bf_hi(unsigned u) { return __uint_as_float(u & 0xffff0000u); }
; __device__ __forceinline__ s16x4 vtr(const LAS unsigned char* p) { return __builtin_bit_cast(s16x4, __builtin_amdgcn_ds_read_tr16_b64_v4i16((LAS s16x4*)p)); }
; __device__ __forceinline__ bf16x8 cat4(s16x4 a, s16x4 b) { return __builtin_shufflevector(a, b, 0, 1, 2, 3, 4, 5, 6, 7); }
; __device__ __forceinline__ void sg_task(const bf16* Z, bf16* YC, const ss_t* ssV, const float* vgain, const float* sw, const float* sb, LAS unsigned char* tile, int task, int tid) {
;     ...
;     for (int cb = 0; cb < 8; ++cb) {
;         f32x4 acc = {0.f, 0.f, 0.f, 0.f};
; #pragma unroll
;         for (int kk = 0; kk < 4; ++kk) { const s16x4 v0 = vtr(tile + tr_addr16(lane, cb, kk, 0)), v1 = vtr(tile + tr_addr16(lane, cb, kk, 1));
;             acc = __builtin_amdgcn_mfma_f32_16x16x32_bf16(cat4(v0, v1), bfrag[kk], acc, 0, 0, 0); }
;         const int c0 = g * 128 + cb * 16 + fq * 4;
;         const f32x4 gn = *(const f32x4*)(vgain + c0);
;         u32x2 w; w.x = cvt_pk_bf16(bf_lo(uu[cb].x) * (acc[0] * gn[0] + bias), bf_hi(uu[cb].x) * (acc[1] * gn[1] + bias));
;         w.y = cvt_pk_bf16(bf_lo(uu[cb].y) * (acc[2] * gn[2] + bias), bf_hi(uu[cb].y) * (acc[3] * gn[3] + bias));
;         *(u32x2*)(YC + tokp * 2048 + 1024 + c0) = w;
;     }
;     __syncthreads();
	v_mfma_f32_16x16x32_bf16 v[18:21], v[22:25], v[6:9], v[18:21]
	v_bitop3_b32 v24, v41, v0, v28 bitop3:0x36
	v_lshl_add_u32 v24, v24, 4, 0
	v_add3_u32 v24, v24, v40, v29
	ds_read_b64_tr_b16 v[22:23], v43 offset:16384
	ds_read_b64_tr_b16 v[24:25], v24
	v_bitop3_b32 v0, v42, v0, v28 bitop3:0x36
	v_lshl_add_u32 v0, v0, 4, 0
	v_add3_u32 v0, v0, v39, v29
	s_waitcnt lgkmcnt(0)
	v_mfma_f32_16x16x32_bf16 v[18:21], v[22:25], v[10:13], v[18:21]
	ds_read_b64_tr_b16 v[22:23], v43 offset:24576
	ds_read_b64_tr_b16 v[24:25], v0
	v_lshlrev_b32_e32 v0, 16, v106
	s_waitcnt lgkmcnt(0)
	v_mfma_f32_16x16x32_bf16 v[18:21], v[22:25], v[14:17], v[18:21]
	v_mov_b32_e32 v22, v60
	v_mov_b32_e32 v23, v61
	v_mov_b32_e32 v24, v62
	v_mov_b32_e32 v25, v63
	s_nop 5
	v_fma_f32 v18, v18, v22, v120
	v_mul_f32_e32 v0, v18, v0
	v_and_b32_e32 v18, 0xffff0000, v106
	v_fma_f32 v19, v19, v23, v120
	v_mul_f32_e32 v18, v19, v18
	v_cvt_pk_bf16_f32 v18, v0, v18
	v_lshlrev_b32_e32 v0, 16, v107
	v_fma_f32 v19, v20, v24, v120
	v_mul_f32_e32 v0, v19, v0
	v_and_b32_e32 v19, 0xffff0000, v107
	v_fma_f32 v20, v21, v25, v120
	v_mul_f32_e32 v19, v20, v19
	v_cvt_pk_bf16_f32 v19, v0, v19
	v_or_b32_e32 v0, 12, v30
	global_store_dwordx2 v[26:27], v[18:19], off offset:2208
	v_bitop3_b32 v18, v30, v32, 12 bitop3:0x36
	v_bitop3_b32 v20, v36, v0, v28 bitop3:0x36
	v_lshlrev_b32_e32 v18, 4, v18
	v_lshl_add_u32 v20, v20, 4, 0
	v_add3_u32 v43, v31, v18, v34
	v_add3_u32 v20, v20, v35, v29
	ds_read_b64_tr_b16 v[18:19], v43
	ds_read_b64_tr_b16 v[20:21], v20
	ds_read_b64_tr_b16 v[22:23], v43 offset:8192
	v_bitop3_b32 v24, v38, v0, v28 bitop3:0x36
	v_lshl_add_u32 v24, v24, 4, 0
	v_add3_u32 v24, v24, v37, v29
	ds_read_b64_tr_b16 v[24:25], v24
	s_waitcnt lgkmcnt(2)
	v_mfma_f32_16x16x32_bf16 v[18:21], v[18:21], v[2:5], 0
	s_waitcnt lgkmcnt(0)
	v_mfma_f32_16x16x32_bf16 v[18:21], v[22:25], v[6:9], v[18:21]
	v_bitop3_b32 v24, v41, v0, v28 bitop3:0x36
	v_lshl_add_u32 v24, v24, 4, 0
	v_add3_u32 v24, v24, v40, v29
	ds_read_b64_tr_b16 v[22:23], v43 offset:16384
	ds_read_b64_tr_b16 v[24:25], v24
	v_bitop3_b32 v0, v42, v0, v28 bitop3:0x36
	v_lshl_add_u32 v0, v0, 4, 0
	v_add3_u32 v0, v0, v39, v29
	s_waitcnt lgkmcnt(0)
	v_mfma_f32_16x16x32_bf16 v[18:21], v[22:25], v[10:13], v[18:21]
	ds_read_b64_tr_b16 v[22:23], v43 offset:24576
	ds_read_b64_tr_b16 v[24:25], v0
	v_lshlrev_b32_e32 v0, 16, v104
	s_waitcnt lgkmcnt(0)
	v_mfma_f32_16x16x32_bf16 v[18:21], v[22:25], v[14:17], v[18:21]
	v_mov_b32_e32 v22, v64
	v_mov_b32_e32 v23, v65
	v_mov_b32_e32 v24, v66
	v_mov_b32_e32 v25, v67
	s_nop 5
	v_fma_f32 v18, v18, v22, v120
	v_mul_f32_e32 v0, v18, v0
	v_and_b32_e32 v18, 0xffff0000, v104
	v_fma_f32 v19, v19, v23, v120
	v_mul_f32_e32 v18, v19, v18
	v_cvt_pk_bf16_f32 v18, v0, v18
	v_lshlrev_b32_e32 v0, 16, v105
	v_fma_f32 v19, v20, v24, v120
	v_mul_f32_e32 v0, v19, v0
	v_and_b32_e32 v19, 0xffff0000, v105
	v_fma_f32 v20, v21, v25, v120
	v_mul_f32_e32 v19, v20, v19
	v_cvt_pk_bf16_f32 v19, v0, v19
	v_or_b32_e32 v0, 14, v30
	global_store_dwordx2 v[26:27], v[18:19], off offset:2240
	v_bitop3_b32 v18, v30, v32, 14 bitop3:0x36
	v_bitop3_b32 v20, v36, v0, v28 bitop3:0x36
	v_lshlrev_b32_e32 v18, 4, v18
	v_lshl_add_u32 v20, v20, 4, 0
	v_add3_u32 v22, v31, v18, v34
	v_add3_u32 v20, v20, v35, v29
	ds_read_b64_tr_b16 v[18:19], v22
	ds_read_b64_tr_b16 v[20:21], v20
	s_waitcnt lgkmcnt(0)
	v_mfma_f32_16x16x32_bf16 v[2:5], v[18:21], v[2:5], 0
	v_bitop3_b32 v20, v38, v0, v28 bitop3:0x36
	v_lshl_add_u32 v20, v20, 4, 0
	v_add3_u32 v20, v20, v37, v29
	ds_read_b64_tr_b16 v[18:19], v22 offset:8192
	ds_read_b64_tr_b16 v[20:21], v20
	s_waitcnt lgkmcnt(0)
	v_mfma_f32_16x16x32_bf16 v[2:5], v[18:21], v[6:9], v[2:5]
	v_bitop3_b32 v8, v41, v0, v28 bitop3:0x36
	v_lshl_add_u32 v8, v8, 4, 0
	v_add3_u32 v8, v8, v40, v29
	ds_read_b64_tr_b16 v[6:7], v22 offset:16384
	ds_read_b64_tr_b16 v[8:9], v8
	v_bitop3_b32 v0, v42, v0, v28 bitop3:0x36
	v_lshl_add_u32 v0, v0, 4, 0
	v_add3_u32 v0, v0, v39, v29
	s_waitcnt lgkmcnt(0)
	v_mfma_f32_16x16x32_bf16 v[2:5], v[6:9], v[10:13], v[2:5]
	ds_read_b64_tr_b16 v[6:7], v22 offset:24576
	ds_read_b64_tr_b16 v[8:9], v0
	v_lshlrev_b32_e32 v0, 16, v102
	s_waitcnt lgkmcnt(0)
	v_mfma_f32_16x16x32_bf16 v[2:5], v[6:9], v[14:17], v[2:5]
	v_mov_b32_e32 v6, v68
	v_mov_b32_e32 v7, v69
	v_mov_b32_e32 v8, v70
	v_mov_b32_e32 v9, v71
	s_nop 5
	v_fma_f32 v2, v2, v6, v120
	v_mul_f32_e32 v0, v2, v0
	v_and_b32_e32 v2, 0xffff0000, v102
	v_fma_f32 v3, v3, v7, v120
	v_mul_f32_e32 v2, v3, v2
	v_cvt_pk_bf16_f32 v2, v0, v2
	v_lshlrev_b32_e32 v0, 16, v103
	v_fma_f32 v3, v4, v8, v120
	v_mul_f32_e32 v0, v3, v0
	v_and_b32_e32 v3, 0xffff0000, v103
	v_fmac_f32_e32 v120, v5, v9
	v_mul_f32_e32 v3, v120, v3
	v_cvt_pk_bf16_f32 v3, v0, v3
	global_store_dwordx2 v[26:27], v[2:3], off offset:2272
	s_barrier
	s_cbranch_scc1 .LBB0_1541
